# P0 rms-row loop: loop-invariant gain loads hoisted out of the per-row loop (removes 4 serialized L2 round trips per row); plus pipelined P14
# baseline (speedup 1.0000x reference)
; __device__ __forceinline__ unsigned cvt_pk_bf16(float lo, float hi) { const f32x2 v = {lo, hi}; const bf16x2_t r = __builtin_convertvector(v, bf16x2_t); return __builtin_bit_cast(unsigned, r); }
; template <bool TILED>
; __device__ __forceinline__ void rms_row_to_bf16(const float* xrow, const float* gain, bf16_t* obase, int m, int lane, float* rsout = nullptr) {
;     f32x4 v[8]; float s = 0.f;
; #pragma unroll
;     for (int j = 0; j < 8; ++j) { v[j] = *(const f32x4*)(xrow + 8 * lane + 512 * (j >> 1) + 4 * (j & 1)); s += (v[j][0] * v[j][0] + v[j][1] * v[j][1]) + (v[j][2] * v[j][2] + v[j][3] * v[j][3]); }
;     const float rs = rsqrtf(wave_sum(s) * (1.0f / 2048.0f) + EPS);
;     if (rsout && lane == 0) rsout[m] = rs;
; #pragma unroll
;     for (int j = 0; j < 4; ++j) { const int c = 8 * lane + 512 * j; const f32x4 g0 = *(const f32x4*)(gain + c), g1 = *(const f32x4*)(gain + c + 4); const f32x4 y0 = v[2 * j] * g0 * rs, y1 = v[2 * j + 1] * g1 * rs;
;         u32x4 w; w.x = cvt_pk_bf16(y0[0], y0[1]); w.y = cvt_pk_bf16(y0[2], y0[3]); w.z = cvt_pk_bf16(y1[0], y1[1]); w.w = cvt_pk_bf16(y1[2], y1[3]);
;         if (TILED) *(u32x4*)(obase + ((size_t)(c >> 6) * T + m) * 64 + (c & 63)) = w; else *(u32x4*)(obase + (size_t)m * D + c) = w; }
; }
; __global__ void __launch_bounds__(NTHR, 2) fwd_megakernel(Params p) {
;     ...
;         for (int m = gw; m < T + MEMT; m += NGW) {
;             if (m < T) rms_row_to_bf16<true>(p.x + (size_t)m * D, p.ffn1_norm, H, m, lane, RS0);
;             else rms_row_to_bf16<false>(p.mem + (size_t)(m - T) * D, p.mem_norm, MEMH, m - T, lane);
;         }
.LBB0_69:
	s_or_b64 exec, exec, s[6:7]
	s_add_u32 s46, s26, 0x984000
	s_addc_u32 s47, s27, 0
	v_readlane_b32 s4, v250, 2
	s_cmpk_gt_i32 s4, 0x41ff
	v_mbcnt_lo_u32_b32 v185, -1, 0
	v_readlane_b32 s5, v250, 3
	s_cbranch_scc1 .LBB0_78
	v_readlane_b32 s48, v251, 21
	v_readlane_b32 s49, v251, 22
	v_readlane_b32 s50, v251, 23
	v_readlane_b32 s51, v251, 24
	v_readlane_b32 s60, v251, 33
	v_readlane_b32 s61, v251, 34
	v_lshlrev_b32_e32 v32, 5, v186
	v_mov_b32_e32 v33, 0
	v_readlane_b32 s64, v251, 1
	v_readlane_b32 s62, v251, 35
	v_readlane_b32 s63, v251, 36
	s_mov_b64 s[48:49], s[60:61]
	v_readlane_b32 s10, v250, 2
	v_readlane_b32 s66, v251, 3
	v_readlane_b32 s67, v251, 4
	v_readlane_b32 s68, v251, 5
	v_readlane_b32 s69, v251, 6
	s_mov_b64 s[50:51], s[62:63]
	v_or_b32_e32 v0, 0x1000, v32
	v_mov_b32_e32 v1, v33
	s_mov_b32 s30, s10
	v_lshl_add_u64 v[34:35], s[66:67], 0, v[32:33]
	v_lshl_add_u64 v[36:37], s[50:51], 0, v[32:33]
	v_lshl_add_u64 v[38:39], s[50:51], 0, v[0:1]
	v_or_b32_e32 v2, 0x1800, v32
	v_mov_b32_e32 v3, v33
	v_lshl_add_u64 v[42:43], s[68:69], 0, v[32:33]
	v_lshl_add_u64 v[44:45], s[68:69], 0, v[0:1]
	v_lshlrev_b32_e32 v32, 4, v186
	v_lshlrev_b32_e32 v0, 18, v184
	s_ashr_i32 s31, s30, 31
	v_lshl_add_u64 v[40:41], s[50:51], 0, v[2:3]
	v_lshl_add_u64 v[46:47], s[68:69], 0, v[2:3]
	v_lshl_add_u64 v[48:49], s[46:47], 0, v[32:33]
	v_and_b32_e32 v32, 0xe00000, v0
	s_lshl_b64 s[20:21], s[30:31], 7
	v_and_b32_e32 v2, 7, v184
	v_lshl_add_u64 v[0:1], v[32:33], 0, s[20:21]
	v_lshlrev_b32_e32 v2, 4, v2
	v_or_b32_e32 v0, v0, v2
	s_mov_b64 s[22:23], 0xcc14000
	v_lshl_add_u64 v[50:51], v[0:1], 0, s[22:23]
	v_or_b32_e32 v0, 0x1000000, v32
	v_mov_b32_e32 v1, v33
	v_lshl_add_u64 v[0:1], v[0:1], 0, s[20:21]
	v_or_b32_e32 v0, v0, v2
	v_lshl_add_u64 v[52:53], v[0:1], 0, s[22:23]
	v_or_b32_e32 v0, 0x2000000, v32
	v_mov_b32_e32 v1, v33
	v_lshl_add_u64 v[0:1], v[0:1], 0, s[20:21]
	s_lshl_b32 s6, s10, 11
	s_ashr_i32 s29, s28, 31
	v_or_b32_e32 v0, v0, v2
	v_or_b32_e32 v32, 0x3000000, v32
	s_add_i32 s10, s6, 0xfe000000
	s_lshl_b32 s19, s34, 14
	s_lshl_b64 s[12:13], s[28:29], 7
	v_lshl_add_u64 v[54:55], v[0:1], 0, s[22:23]
	v_lshl_add_u64 v[0:1], v[32:33], 0, s[20:21]
	s_lshl_b64 s[20:21], s[30:31], 2
	v_or_b32_e32 v0, v0, v2
	s_add_u32 s20, s20, 0x1fc14000
	v_lshl_add_u64 v[56:57], v[0:1], 0, s[22:23]
	s_addc_u32 s21, s21, 0
	s_lshl_b64 s[36:37], s[28:29], 2
	s_lshl_b64 s[22:23], s[30:31], 13
	v_readlane_b32 s65, v251, 2
	v_and_b32_e32 v0, 63, v184
	s_add_u32 s22, s64, s22
	v_lshlrev_b32_e32 v32, 5, v0
	s_addc_u32 s23, s65, s23
	v_lshl_add_u64 v[0:1], s[22:23], 0, v[32:33]
	s_mov_b64 s[22:23], 0x1810
	v_mbcnt_hi_u32_b32 v61, -1, v185
	s_mov_b32 s7, 0
	v_lshl_add_u64 v[58:59], v[0:1], 0, s[22:23]
	s_movk_i32 s48, 0xe7f0
	v_and_b32_e32 v0, 64, v61
	s_mov_b32 s6, s30
	s_movk_i32 s18, 0x1000
	v_cmp_eq_u32_e64 s[4:5], 0, v186
	v_readlane_b32 s11, v250, 3
	s_lshl_b64 s[38:39], s[28:29], 13
	s_mov_b64 s[40:41], 0x1000
	s_mov_b64 s[44:45], 0x1800
	v_mov_b32_e32 v60, 0x358637bd
	s_mov_b32 s22, 0x800000
	s_mov_b32 s49, -1
	v_add_u32_e32 v62, 64, v0
	v_xor_b32_e32 v63, 1, v61
	v_xor_b32_e32 v64, 2, v61
	v_xor_b32_e32 v65, 4, v61
	v_writelane_b32 v250, s6, 2
	s_mov_b32 s23, s30
	v_readlane_b32 s70, v251, 7
	v_readlane_b32 s71, v251, 8
	v_readlane_b32 s72, v251, 9
	v_readlane_b32 s73, v251, 10
	v_readlane_b32 s74, v251, 11
	v_readlane_b32 s75, v251, 12
	v_readlane_b32 s76, v251, 13
	v_readlane_b32 s77, v251, 14
	v_readlane_b32 s78, v251, 15
	v_readlane_b32 s79, v251, 16
	v_readlane_b32 s52, v251, 25
	v_readlane_b32 s53, v251, 26
	v_readlane_b32 s54, v251, 27
	v_readlane_b32 s55, v251, 28
	v_readlane_b32 s56, v251, 29
	v_readlane_b32 s57, v251, 30
	v_readlane_b32 s58, v251, 31
	v_readlane_b32 s59, v251, 32
	v_writelane_b32 v250, s7, 3
	global_load_dwordx4 v[200:203], v[42:43], off
	global_load_dwordx4 v[204:207], v[42:43], off offset:16
	global_load_dwordx4 v[208:211], v[42:43], off offset:2048
	global_load_dwordx4 v[212:215], v[42:43], off offset:2064
	global_load_dwordx4 v[216:219], v[44:45], off
	global_load_dwordx4 v[220:223], v[44:45], off offset:16
	global_load_dwordx4 v[224:227], v[46:47], off
	global_load_dwordx4 v[228:231], v[46:47], off offset:16
	s_branch .LBB0_73
.LBB0_71:
	s_or_b64 exec, exec, s[52:53]
	v_lshl_add_u64 v[74:75], s[26:27], 0, v[50:51]
	v_pk_mul_f32 v[30:31], v[30:31], v[202:203]
	v_pk_mul_f32 v[28:29], v[28:29], v[200:201]
	v_pk_mul_f32 v[26:27], v[26:27], v[206:207]
	v_pk_mul_f32 v[24:25], v[24:25], v[204:205]
	v_pk_mul_f32 v[30:31], v[32:33], v[30:31] op_sel_hi:[0,1]
	v_pk_mul_f32 v[28:29], v[32:33], v[28:29] op_sel_hi:[0,1]
	v_pk_mul_f32 v[66:67], v[32:33], v[26:27] op_sel_hi:[0,1]
	v_pk_mul_f32 v[26:27], v[32:33], v[24:25] op_sel_hi:[0,1]
	v_cvt_pk_bf16_f32 v24, v28, v29
	v_cvt_pk_bf16_f32 v25, v30, v31
	v_cvt_pk_bf16_f32 v26, v26, v27
	v_cvt_pk_bf16_f32 v27, v66, v67
	global_store_dwordx4 v[74:75], v[24:27], off
	s_nop 1
	v_lshl_add_u64 v[66:67], s[26:27], 0, v[52:53]
	v_pk_mul_f32 v[22:23], v[22:23], v[210:211]
	v_pk_mul_f32 v[20:21], v[20:21], v[208:209]
	v_pk_mul_f32 v[18:19], v[18:19], v[214:215]
	v_pk_mul_f32 v[16:17], v[16:17], v[212:213]
	v_pk_mul_f32 v[22:23], v[32:33], v[22:23] op_sel_hi:[0,1]
	v_pk_mul_f32 v[20:21], v[32:33], v[20:21] op_sel_hi:[0,1]
	v_pk_mul_f32 v[24:25], v[32:33], v[18:19] op_sel_hi:[0,1]
	v_pk_mul_f32 v[18:19], v[32:33], v[16:17] op_sel_hi:[0,1]
	v_cvt_pk_bf16_f32 v16, v20, v21
	v_cvt_pk_bf16_f32 v17, v22, v23
	v_cvt_pk_bf16_f32 v18, v18, v19
	v_cvt_pk_bf16_f32 v19, v24, v25
	global_store_dwordx4 v[66:67], v[16:19], off
	s_nop 1
	v_lshl_add_u64 v[24:25], s[26:27], 0, v[54:55]
	v_pk_mul_f32 v[6:7], v[6:7], v[218:219]
	v_pk_mul_f32 v[4:5], v[4:5], v[216:217]
	v_pk_mul_f32 v[2:3], v[2:3], v[222:223]
	v_pk_mul_f32 v[0:1], v[0:1], v[220:221]
	v_pk_mul_f32 v[6:7], v[32:33], v[6:7] op_sel_hi:[0,1]
	v_pk_mul_f32 v[4:5], v[32:33], v[4:5] op_sel_hi:[0,1]
	v_pk_mul_f32 v[16:17], v[32:33], v[2:3] op_sel_hi:[0,1]
	v_pk_mul_f32 v[2:3], v[32:33], v[0:1] op_sel_hi:[0,1]
	v_cvt_pk_bf16_f32 v0, v4, v5
	v_cvt_pk_bf16_f32 v1, v6, v7
	v_cvt_pk_bf16_f32 v2, v2, v3
	v_cvt_pk_bf16_f32 v3, v16, v17
	global_store_dwordx4 v[24:25], v[0:3], off
	s_nop 1
	v_pk_mul_f32 v[2:3], v[14:15], v[226:227]
	v_pk_mul_f32 v[0:1], v[12:13], v[224:225]
	v_pk_mul_f32 v[6:7], v[10:11], v[230:231]
	v_pk_mul_f32 v[4:5], v[8:9], v[228:229]
	v_pk_mul_f32 v[2:3], v[32:33], v[2:3] op_sel_hi:[0,1]
	v_pk_mul_f32 v[0:1], v[32:33], v[0:1] op_sel_hi:[0,1]
	v_pk_mul_f32 v[6:7], v[32:33], v[6:7] op_sel_hi:[0,1]
	v_pk_mul_f32 v[4:5], v[32:33], v[4:5] op_sel_hi:[0,1]
	v_cvt_pk_bf16_f32 v0, v0, v1
	v_cvt_pk_bf16_f32 v1, v2, v3
	v_cvt_pk_bf16_f32 v2, v4, v5
	v_cvt_pk_bf16_f32 v3, v6, v7
	v_lshl_add_u64 v[4:5], s[26:27], 0, v[56:57]
	global_store_dwordx4 v[4:5], v[0:3], off
	s_nop 1
